# v51 plus one shared SGPR base for the K and V LDS-DMA streams (V through a constant-offset VGPR) and one hazard nop replaced by useful scalar work
# speedup vs baseline: 1.0057x; 1.0023x over previous
; __device__ __forceinline__ int otid() { int t = threadIdx.x; asm volatile("" : "+v"(t)); return t; }
; #define WAIT_BAR(N) asm volatile("s_waitcnt vmcnt(" #N ") lgkmcnt(0)\n\ts_barrier":::"memory")
;   #define DMA_K(t,slot) glds16(ksrc+(long)(t)*KVBLK*KVP,(unsigned)__builtin_amdgcn_readfirstlane(kdst+(slot)))
;   #define DMA_V(t,slot) glds16(vsrc+(long)(t)*KVBLK*KVP,(unsigned)__builtin_amdgcn_readfirstlane(vdst+(slot)))
;   #define CMASK(P0,P1,t) do{}while(0)
;   #define CMASK(P0,P1,t) do{}while(0)
;   #define CMASK(P0,P1,t) do{}while(0)
; template<int THRL> __device__ __forceinline__ void attn_unit(const bf16*Qu,const bf16*__restrict__ Kh,const bf16*__restrict__ Vh,bf16*Ou,const int NT,const float shift,char*shm){
;   const int tid=otid(),lane=tid&63,r32=lane&31,hi=lane>>5; const int wid=__builtin_amdgcn_readfirstlane(tid>>6);
;   const bf16*Qw=Qu+(long)wid*QBLK*QP;
;   const unsigned lds0=(unsigned)(uintptr_t)shm;
;   float*wsf=(float*)(shm+LDS_WS)+wid*64;
;   const bf16*ksrc=Kh+(long)lane*KVP+wid*8;
;   const bf16*vsrc=Vh+(long)(16*(wid&3)+(lane>>2))*KVP+(wid>>2)*32+(lane&3)*8;
;   const unsigned kdst=lds0+LDS_K+wid*1024, vdst=lds0+LDS_V+wid*1024;
;     ...
;   const int vb0=(int)(lds0+LDS_V)+((lane>>4)&1)*32+(lane&3)*8+(4*hi+((lane&15)>>2))*64;
;   const char*Kbase=shm+LDS_K; bf16x8 kf[8];
;   const lds_cptr shm3=(lds_cptr)shm; const lds_cptr kp0=shm3+LDS_K+hi*1024+r32*16; const lds_cptr vp0=shm3+LDS_V+((lane>>4)&1)*32+(lane&3)*8+(4*hi+((lane&15)>>2))*64;
;   DMA_K(0,0);DMA_V(0,0);DMA_K(1,SLOTB);
;   bf16x8 qr[4];
;   #pragma unroll
;   for(int d0=0;d0<4;++d0)qr[d0]=*reinterpret_cast<const bf16x8*>(&Qw[(long)r32*QP+d0*16+hi*8]);
;   float mhat=0.f,l_reg=0.f;f32x16 o[2];o[0]=f32x16{};o[1]=f32x16{};f32x16 negm=f32x16{};asm volatile("":"+v"(negm));
;     ...
;   bool resc=false;
;     ...
;   f32x16 pA0,pA1,pB0,pB1;
;   int sl_prev=0,sl_cur=0,sl_next=SLOTB;
;     ...
;   DMA_K(2,2*SLOTB);
;   WAIT_BAR(3);
;   qkt(pA0,pA1,Kbase,qr,negm,r32,hi);asm volatile("s_nop 15\n\ts_nop 7":"+v"(pA0),"+v"(pA1));CMASK(pA0,pA1,0);
;   START(pA0,pA1);
;   _Pragma("unroll") for(int r=0;r<16;++r)pA1[r]=__builtin_amdgcn_exp2f(pA1[r]);
;   WAIT_BAR(0);
.LBB0_616:
	s_lshl_b32 s4, s84, 1
	s_ashr_i32 s5, s82, 2
	s_add_i32 s6, s4, s5
	v_readlane_b32 s4, v246, 62
	v_readlane_b32 s5, v246, 63
	s_lshl_b64 s[4:5], s[4:5], 11
	s_add_u32 s7, s57, s4
	s_addc_u32 s24, s58, s5
	s_lshl_b32 s4, s82, 6
	s_ashr_i32 s5, s4, 31
	s_lshl_b64 s[48:49], s[4:5], 1
	s_add_u32 s26, s7, s48
	s_addc_u32 s27, s24, s49
	s_mul_hi_i32 s7, s6, 0x208000
	s_mul_i32 s6, s6, 0x208000
	s_add_u32 s4, s59, s6
	s_addc_u32 s5, s60, s7
	v_mov_b32_e32 v42, v216
	s_add_u32 s6, s61, s6
	s_addc_u32 s7, s62, s7
	v_readfirstlane_b32 s69, v42
	s_ashr_i32 s44, s69, 6
	s_ashr_i32 s45, s44, 31
	v_and_b32_e32 v238, 63, v42
	s_lshl_b64 s[24:25], s[44:45], 16
	s_add_u32 s24, s26, s24
	v_lshlrev_b32_e32 v0, 4, v42
	s_addc_u32 s25, s27, s25
	v_lshl_add_u64 v[2:3], s[4:5], 0, v[0:1]
	s_mov_b32 s4, 0
	s_ashr_i32 s5, s4, 31
	v_lshl_add_u64 v[212:213], s[4:5], 1, v[2:3]
	s_lshl_b32 s4, s44, 4
	v_bfe_u32 v0, v42, 2, 4
	v_and_or_b32 v0, s4, 48, v0
	s_ashr_i32 s4, s69, 3
	s_andn2_b32 s4, s4, 31
	v_lshlrev_b32_e32 v0, 7, v0
	s_ashr_i32 s5, s4, 31
	s_lshl_b32 s70, s44, 10
	v_lshl_add_u64 v[2:3], s[6:7], 0, v[0:1]
	v_lshlrev_b32_e32 v239, 3, v42
	s_cmp_lg_u32 0, -1
	v_lshl_add_u64 v[2:3], s[4:5], 1, v[2:3]
	v_and_b32_e32 v242, 24, v239
	s_cselect_b32 s4, 0, 0
	v_and_b32_e32 v240, 31, v42
	v_lshlrev_b32_e32 v0, 4, v42
	s_add_i32 s70, s70, s4
	s_mov_b32 s4, m0
	s_mov_b32 m0, s70
	s_nop 0
	global_load_lds_dwordx4 v[212:213], off
	s_mov_b32 m0, s4
	v_bfe_u32 v241, v42, 5, 1
	v_lshl_add_u64 v[214:215], s[6:7], 0, v[0:1]
	s_add_i32 s71, s70, 0x6000
	s_mov_b32 s4, m0
	s_mov_b32 m0, s71
	s_nop 0
	global_load_lds_dwordx4 v[214:215], off
	s_mov_b32 m0, s4
	s_mov_b64 s[26:27], 0x2000
	v_lshlrev_b32_e32 v0, 11, v240
	v_lshl_add_u64 v[2:3], v[212:213], 0, s[26:27]
	s_add_i32 s4, s70, 0x2000
	s_mov_b32 s5, m0
	s_mov_b32 m0, s4
	s_nop 0
	global_load_lds_dwordx4 v[2:3], off
	s_mov_b32 m0, s5
	v_lshl_or_b32 v0, v241, 4, v0
	global_load_dwordx4 v[150:153], v0, s[24:25]
	global_load_dwordx4 v[138:141], v0, s[24:25] offset:32
	global_load_dwordx4 v[134:137], v0, s[24:25] offset:64
	global_load_dwordx4 v[130:133], v0, s[24:25] offset:96
	v_mov_b32_e32 v2, v1
	v_mov_b32_e32 v3, v1
	v_mov_b32_e32 v4, v1
	v_mov_b32_e32 v5, v1
	v_mov_b32_e32 v6, v1
	v_mov_b32_e32 v7, v1
	v_mov_b32_e32 v8, v1
	v_mov_b32_e32 v9, v1
	v_mov_b32_e32 v10, v1
	v_mov_b32_e32 v11, v1
	v_mov_b32_e32 v12, v1
	v_mov_b32_e32 v13, v1
	v_mov_b32_e32 v14, v1
	v_mov_b32_e32 v15, v1
	v_lshlrev_b32_e32 v0, 10, v241
	v_lshlrev_b32_e32 v16, 4, v240
	v_add3_u32 v244, 0, v0, v16
	v_mov_b32_e32 v0, v1
	v_mov_b64_e32 v[16:17], v[14:15]
	v_mov_b64_e32 v[14:15], v[12:13]
	v_mov_b64_e32 v[12:13], v[10:11]
	v_mov_b64_e32 v[10:11], v[8:9]
	v_mov_b64_e32 v[8:9], v[6:7]
	v_mov_b64_e32 v[6:7], v[4:5]
	v_mov_b64_e32 v[4:5], v[2:3]
	v_mov_b64_e32 v[2:3], v[0:1]
	v_lshl_add_u64 v[18:19], v[212:213], 0, s[72:73]
	s_add_i32 s4, s70, 0x4000
	s_mov_b32 s5, m0
	s_mov_b32 m0, s4
	s_nop 0
	global_load_lds_dwordx4 v[18:19], off
	s_mov_b32 m0, s5
	s_waitcnt vmcnt(3) lgkmcnt(0)
	s_barrier
	ds_read_b128 v[34:37], v244
	ds_read_b128 v[38:41], v244 offset:512
	v_lshlrev_b32_e32 v0, 1, v42
	v_and_b32_e32 v243, 32, v0
	s_mov_b64 s[34:35], 0x6000
	v_add_u32_e32 v50, 0, v243
	s_mov_b32 s5, 1
	s_mov_b32 s4, 0
	s_movk_i32 s31, 0x2000
	s_mov_b32 s24, 0
	s_movk_i32 s76, 0x4000
	s_waitcnt vmcnt(3) lgkmcnt(1)
	v_mfma_f32_32x32x16_bf16 v[18:33], v[34:37], v[150:153], v[2:17]
	s_waitcnt lgkmcnt(0)
	v_mfma_f32_32x32x16_bf16 v[2:17], v[38:41], v[150:153], v[2:17]
	ds_read_b128 v[34:37], v244 offset:2048
	ds_read_b128 v[38:41], v244 offset:2560
	s_waitcnt vmcnt(2) lgkmcnt(1)
	v_mfma_f32_32x32x16_bf16 v[18:33], v[34:37], v[138:141], v[18:33]
	s_waitcnt lgkmcnt(0)
	v_mfma_f32_32x32x16_bf16 v[2:17], v[38:41], v[138:141], v[2:17]
	ds_read_b128 v[34:37], v244 offset:4096
	ds_read_b128 v[38:41], v244 offset:4608
	s_waitcnt vmcnt(1) lgkmcnt(1)
	v_mfma_f32_32x32x16_bf16 v[18:33], v[34:37], v[134:137], v[18:33]
	ds_read_b128 v[34:37], v244 offset:6144
	s_waitcnt lgkmcnt(1)
	v_mfma_f32_32x32x16_bf16 v[2:17], v[38:41], v[134:137], v[2:17]
	ds_read_b128 v[38:41], v244 offset:6656
	s_waitcnt vmcnt(0) lgkmcnt(1)
	v_mfma_f32_32x32x16_bf16 v[18:33], v[34:37], v[130:133], v[18:33]
	v_add_f32_e32 v34, v1, v237
	v_lshlrev_b32_e32 v35, 4, v42
	v_xor_b32_e32 v34, 0x80000000, v34
	v_and_b32_e32 v0, 0xc0, v35
	v_mov_b32_e32 v35, v34
	v_mov_b32_e32 v36, v34
	v_mov_b32_e32 v37, v34
	s_waitcnt lgkmcnt(0)
	v_mfma_f32_32x32x16_bf16 v[2:17], v[38:41], v[130:133], v[2:17]
	s_nop 15
	s_nop 7
	v_mov_b32_e32 v38, v34
	v_mov_b32_e32 v39, v34
	v_mov_b32_e32 v40, v34
	v_mov_b32_e32 v41, v34
	v_mov_b32_e32 v42, v34
	v_mov_b32_e32 v43, v34
	v_mov_b32_e32 v44, v34
	v_mov_b32_e32 v45, v34
	v_mov_b32_e32 v46, v34
	v_mov_b32_e32 v47, v34
	v_mov_b32_e32 v48, v34
	v_mov_b32_e32 v49, v34
	v_sub_f32_e32 v2, v2, v237
	v_sub_f32_e32 v3, v3, v237
	s_waitcnt vmcnt(0) lgkmcnt(0)
	s_barrier
; #define WAIT_BAR(N) asm volatile("s_waitcnt vmcnt(" #N ") lgkmcnt(0)\n\ts_barrier":::"memory")
;   #define DMA_K(t,slot) glds16(ksrc+(long)(t)*KVBLK*KVP,(unsigned)__builtin_amdgcn_readfirstlane(kdst+(slot)))
;   #define DMA_V(t,slot) glds16(vsrc+(long)(t)*KVBLK*KVP,(unsigned)__builtin_amdgcn_readfirstlane(vdst+(slot)))
;   #define ROT() do{sl_prev=sl_cur;sl_cur=sl_next;sl_next=(sl_next==(NSLOT-1)*SLOTB)?0:sl_next+SLOTB;}while(0)
; template<int THRL> __device__ __forceinline__ void attn_unit(const bf16*Qu,const bf16*__restrict__ Kh,const bf16*__restrict__ Vh,bf16*Ou,const int NT,const float shift,char*shm){
;     ...
;   _Pragma("unroll") for(int r=0;r<16;++r)pA1[r]=__builtin_amdgcn_exp2f(pA1[r]);
;   WAIT_BAR(0);
;   DMA_K(3,0);DMA_V(1,SLOTB);
;   ROT();
;   kload8(kf,kp0+sl_cur);
;   WAIT_BAR(2);
;   s16x4 vlo[8],vhi[8]; u32x4 pw0,pw1,pw2,pw3;
;     ...
;   int t=1;
;     ...
;   for(;t+5<NT;t+=2){
	v_sub_f32_e32 v18, v18, v237
	v_sub_f32_e32 v19, v19, v237
	s_nop 0
	v_exp_f32_e32 v66, v2
	v_exp_f32_e32 v67, v3
	v_lshl_add_u64 v[2:3], v[212:213], 0, s[34:35]
	s_mov_b32 s6, m0
	s_mov_b32 m0, s70
	s_nop 0
	global_load_lds_dwordx4 v[2:3], off
	s_mov_b32 m0, s6
	v_lshl_add_u64 v[2:3], v[214:215], 0, s[26:27]
	s_add_i32 s6, s70, 0x8000
	s_mov_b32 s7, m0
	s_mov_b32 m0, s6
	s_nop 0
	global_load_lds_dwordx4 v[2:3], off
	s_mov_b32 m0, s7
	ds_read_b128 v[190:193], v244 offset:8192
	ds_read_b128 v[186:189], v244 offset:8704
	ds_read_b128 v[182:185], v244 offset:10240
	ds_read_b128 v[178:181], v244 offset:10752
	ds_read_b128 v[174:177], v244 offset:12288
	ds_read_b128 v[170:173], v244 offset:12800
	ds_read_b128 v[166:169], v244 offset:14336
	ds_read_b128 v[162:165], v244 offset:14848
	v_sub_f32_e32 v20, v20, v237
	v_sub_f32_e32 v4, v4, v237
	v_sub_f32_e32 v21, v21, v237
	v_sub_f32_e32 v5, v5, v237
	v_sub_f32_e32 v22, v22, v237
	v_sub_f32_e32 v6, v6, v237
	v_sub_f32_e32 v23, v23, v237
	v_sub_f32_e32 v7, v7, v237
	v_sub_f32_e32 v24, v24, v237
	v_sub_f32_e32 v8, v8, v237
	v_sub_f32_e32 v25, v25, v237
	v_sub_f32_e32 v9, v9, v237
	v_sub_f32_e32 v26, v26, v237
	v_sub_f32_e32 v10, v10, v237
	v_sub_f32_e32 v27, v27, v237
	v_sub_f32_e32 v11, v11, v237
	v_sub_f32_e32 v28, v28, v237
	v_sub_f32_e32 v12, v12, v237
	v_sub_f32_e32 v29, v29, v237
	v_sub_f32_e32 v13, v13, v237
	v_sub_f32_e32 v30, v30, v237
	v_sub_f32_e32 v14, v14, v237
	v_sub_f32_e32 v31, v31, v237
	v_sub_f32_e32 v15, v15, v237
	v_sub_f32_e32 v32, v32, v237
	v_sub_f32_e32 v16, v16, v237
	v_sub_f32_e32 v33, v33, v237
	v_sub_f32_e32 v17, v17, v237
	v_exp_f32_e32 v82, v18
	v_exp_f32_e32 v83, v19
	v_exp_f32_e32 v84, v20
	v_exp_f32_e32 v85, v21
	v_exp_f32_e32 v86, v22
	v_exp_f32_e32 v87, v23
	v_exp_f32_e32 v88, v24
	v_exp_f32_e32 v89, v25
	v_exp_f32_e32 v90, v26
	v_exp_f32_e32 v91, v27
	v_exp_f32_e32 v92, v28
	v_exp_f32_e32 v93, v29
	v_exp_f32_e32 v94, v30
	v_exp_f32_e32 v95, v31
	v_exp_f32_e32 v96, v32
	v_exp_f32_e32 v97, v33
	v_exp_f32_e32 v68, v4
	v_exp_f32_e32 v69, v5
	v_exp_f32_e32 v70, v6
	v_exp_f32_e32 v71, v7
	v_exp_f32_e32 v72, v8
	v_exp_f32_e32 v73, v9
	v_exp_f32_e32 v74, v10
	v_exp_f32_e32 v75, v11
	v_exp_f32_e32 v76, v12
	v_exp_f32_e32 v77, v13
	v_exp_f32_e32 v78, v14
	v_exp_f32_e32 v79, v15
	v_exp_f32_e32 v80, v16
	v_exp_f32_e32 v81, v17
	s_waitcnt vmcnt(2) lgkmcnt(0)
	s_barrier
	v_lshl_or_b32 v0, v241, 8, v0
	v_add3_u32 v245, v50, v242, v0
	s_cmp_lt_i32 s91, 6
	s_cbranch_scc1 .LBB0_620
	s_mov_b64 s[4:5], 0xa000
	v_mov_b32_e32 v199, v245
	v_add_u32_e32 v200, 0x2000, v245
	v_add_u32_e32 v201, 0x4000, v245
	v_mov_b32_e32 v202, v244
	v_add_u32_e32 v203, 0x2000, v244
	v_add_u32_e32 v204, 0x4000, v244
	v_mov_b32_e32 v50, 0
	v_mov_b32_e32 v194, 0
	v_mov_b32_e32 v195, 0
	v_mov_b32_e32 v196, 0
	v_lshlrev_b32_e32 v197, 4, v238
	v_readfirstlane_b32 s98, v212
	v_readfirstlane_b32 s99, v213
	v_readfirstlane_b32 s100, v214
	v_readfirstlane_b32 s101, v215
	s_add_u32 s98, s98, 0x8000
	s_addc_u32 s99, s99, 0
	s_add_u32 s100, s100, 0x4000
	s_addc_u32 s101, s101, 0
	s_sub_u32 s6, s100, s98
	v_add_u32_e32 v205, s6, v197
	s_mov_b32 s26, 6
	v_mov_b32_e32 v2, 0
	v_mov_b32_e32 v3, v50
	v_mov_b32_e32 v4, v50
	v_mov_b32_e32 v5, v50
	v_mov_b32_e32 v6, v50
	v_mov_b32_e32 v7, v50
	v_mov_b32_e32 v8, v50
	v_mov_b32_e32 v9, v50
	v_mov_b32_e32 v10, v50
	v_mov_b32_e32 v11, v50
	v_mov_b32_e32 v12, v50
	v_mov_b32_e32 v13, v50
	v_mov_b32_e32 v14, v50
	v_mov_b32_e32 v15, v50
	v_mov_b32_e32 v16, v50
	v_mov_b32_e32 v17, v50
	v_mov_b32_e32 v18, 0
	v_mov_b32_e32 v19, v50
	v_mov_b32_e32 v20, v50
	v_mov_b32_e32 v21, v50
	v_mov_b32_e32 v22, v50
	v_mov_b32_e32 v23, v50
	v_mov_b32_e32 v24, v50
	v_mov_b32_e32 v25, v50
	v_mov_b32_e32 v26, v50
	v_mov_b32_e32 v27, v50
	v_mov_b32_e32 v28, v50
	v_mov_b32_e32 v29, v50
	v_mov_b32_e32 v30, v50
	v_mov_b32_e32 v31, v50
	v_mov_b32_e32 v32, v50
	v_mov_b32_e32 v33, v50
	s_branch .LBB0_618

.LBB0_618:
	ds_read_b64_tr_b16 v[52:53], v199 offset:24576
	ds_read_b64_tr_b16 v[54:55], v199 offset:25088
	v_mfma_f32_32x32x16_bf16 v[114:129], v[190:193], v[150:153], v[34:49]
	v_add_f32_e32 v50, v82, v50
	v_add_f32_e32 v194, v83, v194
	v_add_f32_e32 v195, v84, v195
	v_add_f32_e32 v196, v85, v196
	v_add_f32_e32 v50, v86, v50
	v_add_f32_e32 v194, v87, v194
	v_cvt_pk_bf16_f32 v158, v82, v83
	v_cvt_pk_bf16_f32 v159, v84, v85
	ds_read_b64_tr_b16 v[60:61], v199 offset:28672
	ds_read_b64_tr_b16 v[62:63], v199 offset:29184
	v_mfma_f32_32x32x16_bf16 v[98:113], v[186:189], v[150:153], v[34:49]
	v_add_f32_e32 v195, v88, v195
	v_add_f32_e32 v196, v89, v196
	v_add_f32_e32 v50, v90, v50
	v_add_f32_e32 v194, v91, v194
	v_cvt_pk_bf16_f32 v160, v86, v87
	v_cvt_pk_bf16_f32 v161, v88, v89
	ds_read_b64_tr_b16 v[82:83], v199 offset:25600
	ds_read_b64_tr_b16 v[84:85], v199 offset:26112
	v_mfma_f32_32x32x16_bf16 v[114:129], v[182:185], v[138:141], v[114:129]
	v_add_f32_e32 v195, v92, v195
	v_add_f32_e32 v196, v93, v196
	v_add_f32_e32 v50, v94, v50
	v_add_f32_e32 v194, v95, v194
	v_cvt_pk_bf16_f32 v154, v90, v91
	v_cvt_pk_bf16_f32 v155, v92, v93
	ds_read_b64_tr_b16 v[86:87], v199 offset:29696
	ds_read_b64_tr_b16 v[88:89], v199 offset:30208
	v_mfma_f32_32x32x16_bf16 v[98:113], v[178:181], v[138:141], v[98:113]
	v_add_f32_e32 v195, v96, v195
	v_add_f32_e32 v196, v97, v196
	v_add_f32_e32 v50, v66, v50
	v_add_f32_e32 v194, v67, v194
	v_cvt_pk_bf16_f32 v156, v94, v95
	v_cvt_pk_bf16_f32 v157, v96, v97
	ds_read_b64_tr_b16 v[90:91], v199 offset:26624
	ds_read_b64_tr_b16 v[92:93], v199 offset:27136
	v_mfma_f32_32x32x16_bf16 v[114:129], v[174:177], v[134:137], v[114:129]
	v_add_f32_e32 v195, v68, v195
	v_add_f32_e32 v196, v69, v196
	v_add_f32_e32 v50, v70, v50
	v_add_f32_e32 v194, v71, v194
	v_cvt_pk_bf16_f32 v146, v66, v67
	v_cvt_pk_bf16_f32 v147, v68, v69
	ds_read_b64_tr_b16 v[64:65], v199 offset:30720
	ds_read_b64_tr_b16 v[66:67], v199 offset:31232
	v_mfma_f32_32x32x16_bf16 v[98:113], v[170:173], v[134:137], v[98:113]
	v_add_f32_e32 v195, v72, v195
	v_add_f32_e32 v196, v73, v196
	v_add_f32_e32 v50, v74, v50
	v_add_f32_e32 v194, v75, v194
	v_cvt_pk_bf16_f32 v148, v70, v71
	v_cvt_pk_bf16_f32 v149, v72, v73
	ds_read_b64_tr_b16 v[68:69], v199 offset:27648
	ds_read_b64_tr_b16 v[70:71], v199 offset:28160
	v_mfma_f32_32x32x16_bf16 v[114:129], v[166:169], v[130:133], v[114:129]
	v_add_f32_e32 v195, v76, v195
	v_add_f32_e32 v196, v77, v196
	v_add_f32_e32 v50, v78, v50
	v_add_f32_e32 v194, v79, v194
	v_cvt_pk_bf16_f32 v142, v74, v75
	v_cvt_pk_bf16_f32 v143, v76, v77
	ds_read_b64_tr_b16 v[72:73], v199 offset:31744
	ds_read_b64_tr_b16 v[74:75], v199 offset:32256
	v_mfma_f32_32x32x16_bf16 v[98:113], v[162:165], v[130:133], v[98:113]
	v_add_f32_e32 v195, v80, v195
	v_add_f32_e32 v196, v81, v196
	v_cvt_pk_bf16_f32 v144, v78, v79
	v_cvt_pk_bf16_f32 v145, v80, v81
	s_add_i32 m0, s31, s70
	s_add_i32 s6, s76, s71
	global_load_lds_dwordx4 v197, s[98:99]
	s_mov_b32 m0, s6
	s_nop 0
	global_load_lds_dwordx4 v205, s[98:99]
	s_add_u32 s98, s98, 0x2000
	s_addc_u32 s99, s99, 0
	s_waitcnt lgkmcnt(14)
	v_mfma_f32_32x32x16_bf16 v[2:17], v[158:161], v[52:55], v[2:17]
	v_exp_f32_e32 v114, v114
	v_exp_f32_e32 v115, v115
	v_exp_f32_e32 v116, v116
	v_exp_f32_e32 v117, v117
	s_waitcnt lgkmcnt(12)
	v_mfma_f32_32x32x16_bf16 v[18:33], v[158:161], v[60:63], v[18:33]
	v_exp_f32_e32 v118, v118
	v_exp_f32_e32 v119, v119
	v_exp_f32_e32 v120, v120
	v_exp_f32_e32 v121, v121
	ds_read_b128 v[60:63], v204
	ds_read_b128 v[162:165], v204 offset:512
	s_waitcnt lgkmcnt(12)
	v_mfma_f32_32x32x16_bf16 v[2:17], v[154:157], v[82:85], v[2:17]
	v_exp_f32_e32 v122, v122
	v_exp_f32_e32 v123, v123
	v_exp_f32_e32 v124, v124
	v_exp_f32_e32 v125, v125
	ds_read_b128 v[166:169], v204 offset:2048
	ds_read_b128 v[170:173], v204 offset:2560
	s_waitcnt lgkmcnt(12)
	v_mfma_f32_32x32x16_bf16 v[18:33], v[154:157], v[86:89], v[18:33]
	v_exp_f32_e32 v126, v126
	v_exp_f32_e32 v127, v127
	v_exp_f32_e32 v128, v128
	v_exp_f32_e32 v129, v129
	ds_read_b128 v[174:177], v204 offset:4096
	ds_read_b128 v[178:181], v204 offset:4608
	s_waitcnt lgkmcnt(12)
	v_mfma_f32_32x32x16_bf16 v[2:17], v[146:149], v[90:93], v[2:17]
	v_exp_f32_e32 v98, v98
	v_exp_f32_e32 v99, v99
	v_exp_f32_e32 v100, v100
	v_exp_f32_e32 v101, v101
	ds_read_b128 v[182:185], v204 offset:6144
	ds_read_b128 v[52:55], v204 offset:6656
	s_waitcnt lgkmcnt(12)
	v_mfma_f32_32x32x16_bf16 v[18:33], v[146:149], v[64:67], v[18:33]
	v_exp_f32_e32 v102, v102
	v_exp_f32_e32 v103, v103
	v_exp_f32_e32 v104, v104
	v_exp_f32_e32 v105, v105
	s_waitcnt lgkmcnt(10)
	v_mfma_f32_32x32x16_bf16 v[2:17], v[142:145], v[68:71], v[2:17]
	v_exp_f32_e32 v106, v106
	v_exp_f32_e32 v107, v107
	v_exp_f32_e32 v108, v108
	v_exp_f32_e32 v109, v109
	s_waitcnt lgkmcnt(8)
	v_mfma_f32_32x32x16_bf16 v[18:33], v[142:145], v[72:75], v[18:33]
	v_exp_f32_e32 v110, v110
	v_exp_f32_e32 v111, v111
	v_exp_f32_e32 v112, v112
	v_exp_f32_e32 v113, v113
	s_add_i32 s6, s76, 0x2000
	s_cmpk_lg_i32 s76, 0x4000
	s_cselect_b32 s31, s6, 0
	s_waitcnt vmcnt(2) lgkmcnt(0)
	s_barrier
; #define WAIT_BAR(N) asm volatile("s_waitcnt vmcnt(" #N ") lgkmcnt(0)\n\ts_barrier":::"memory")
;   #define RESC() do{ if(resc){ asm volatile("s_waitcnt lgkmcnt(0)":::"memory"); \
;       _Pragma("unroll") for(int d_=0;d_<2;++d_) _Pragma("unroll") for(int r=0;r<16;++r)o[d_][r]*=wsf[crow(r,hi)]; } }while(0)
;   #define ROT() do{sl_prev=sl_cur;sl_cur=sl_next;sl_next=(sl_next==(NSLOT-1)*SLOTB)?0:sl_next+SLOTB;}while(0)
; template<int THRL> __device__ __forceinline__ void attn_unit(const bf16*Qu,const bf16*__restrict__ Kh,const bf16*__restrict__ Vh,bf16*Ou,const int NT,const float shift,char*shm){
;     ...
;     STEP(pB0,pB1,pA0,pA1,t,true,true,true);     WAIT_BAR(2); RESC(); ROT();
;     STEP(pA0,pA1,pB0,pB1,t+1,true,true,true);   WAIT_BAR(2); RESC(); ROT();
	ds_read_b64_tr_b16 v[186:187], v200 offset:24576
	ds_read_b64_tr_b16 v[188:189], v200 offset:25088
	v_mfma_f32_32x32x16_bf16 v[82:97], v[60:63], v[150:153], v[34:49]
	v_add_f32_e32 v50, v114, v50
	v_add_f32_e32 v194, v115, v194
	v_add_f32_e32 v195, v116, v195
	v_add_f32_e32 v196, v117, v196
	v_add_f32_e32 v50, v118, v50
	v_add_f32_e32 v194, v119, v194
	v_cvt_pk_bf16_f32 v158, v114, v115
	v_cvt_pk_bf16_f32 v159, v116, v117
	ds_read_b64_tr_b16 v[60:61], v200 offset:28672
	ds_read_b64_tr_b16 v[62:63], v200 offset:29184
	v_mfma_f32_32x32x16_bf16 v[66:81], v[162:165], v[150:153], v[34:49]
	v_add_f32_e32 v195, v120, v195
	v_add_f32_e32 v196, v121, v196
	v_add_f32_e32 v50, v122, v50
	v_add_f32_e32 v194, v123, v194
	v_cvt_pk_bf16_f32 v160, v118, v119
	v_cvt_pk_bf16_f32 v161, v120, v121
	ds_read_b64_tr_b16 v[114:115], v200 offset:25600
	ds_read_b64_tr_b16 v[116:117], v200 offset:26112
	v_mfma_f32_32x32x16_bf16 v[82:97], v[166:169], v[138:141], v[82:97]
	v_add_f32_e32 v195, v124, v195
	v_add_f32_e32 v196, v125, v196
	v_add_f32_e32 v50, v126, v50
	v_add_f32_e32 v194, v127, v194
	v_cvt_pk_bf16_f32 v154, v122, v123
	v_cvt_pk_bf16_f32 v155, v124, v125
	ds_read_b64_tr_b16 v[118:119], v200 offset:29696
	ds_read_b64_tr_b16 v[120:121], v200 offset:30208
	v_mfma_f32_32x32x16_bf16 v[66:81], v[170:173], v[138:141], v[66:81]
	v_add_f32_e32 v195, v128, v195
	v_add_f32_e32 v196, v129, v196
	v_add_f32_e32 v50, v98, v50
	v_add_f32_e32 v194, v99, v194
	v_cvt_pk_bf16_f32 v156, v126, v127
	v_cvt_pk_bf16_f32 v157, v128, v129
	ds_read_b64_tr_b16 v[122:123], v200 offset:26624
	ds_read_b64_tr_b16 v[124:125], v200 offset:27136
	v_mfma_f32_32x32x16_bf16 v[82:97], v[174:177], v[134:137], v[82:97]
	v_add_f32_e32 v195, v100, v195
	v_add_f32_e32 v196, v101, v196
	v_add_f32_e32 v50, v102, v50
	v_add_f32_e32 v194, v103, v194
	v_cvt_pk_bf16_f32 v146, v98, v99
	v_cvt_pk_bf16_f32 v147, v100, v101
	ds_read_b64_tr_b16 v[98:99], v200 offset:30720
	ds_read_b64_tr_b16 v[100:101], v200 offset:31232
	v_mfma_f32_32x32x16_bf16 v[66:81], v[178:181], v[134:137], v[66:81]
	v_add_f32_e32 v195, v104, v195
	v_add_f32_e32 v196, v105, v196
	v_add_f32_e32 v50, v106, v50
	v_add_f32_e32 v194, v107, v194
	v_cvt_pk_bf16_f32 v148, v102, v103
	v_cvt_pk_bf16_f32 v149, v104, v105
	ds_read_b64_tr_b16 v[102:103], v200 offset:27648
	ds_read_b64_tr_b16 v[104:105], v200 offset:28160
	v_mfma_f32_32x32x16_bf16 v[82:97], v[182:185], v[130:133], v[82:97]
	v_add_f32_e32 v195, v108, v195
	v_add_f32_e32 v196, v109, v196
	v_add_f32_e32 v50, v110, v50
	v_add_f32_e32 v194, v111, v194
	v_cvt_pk_bf16_f32 v142, v106, v107
	v_cvt_pk_bf16_f32 v143, v108, v109
	ds_read_b64_tr_b16 v[106:107], v200 offset:31744
	ds_read_b64_tr_b16 v[108:109], v200 offset:32256
	v_mfma_f32_32x32x16_bf16 v[66:81], v[52:55], v[130:133], v[66:81]
	v_add_f32_e32 v195, v112, v195
	v_add_f32_e32 v196, v113, v196
	v_cvt_pk_bf16_f32 v144, v110, v111
	v_cvt_pk_bf16_f32 v145, v112, v113
	s_add_i32 m0, s76, s70
	s_add_i32 s6, s31, s71
	global_load_lds_dwordx4 v197, s[98:99]
	s_mov_b32 m0, s6
	s_nop 0
	global_load_lds_dwordx4 v205, s[98:99]
	s_add_u32 s98, s98, 0x2000
	s_addc_u32 s99, s99, 0
	s_waitcnt lgkmcnt(14)
	v_mfma_f32_32x32x16_bf16 v[2:17], v[158:161], v[186:189], v[2:17]
	v_exp_f32_e32 v82, v82
	v_exp_f32_e32 v83, v83
	v_exp_f32_e32 v84, v84
	v_exp_f32_e32 v85, v85
	s_waitcnt lgkmcnt(12)
	v_mfma_f32_32x32x16_bf16 v[18:33], v[158:161], v[60:63], v[18:33]
	v_exp_f32_e32 v86, v86
	v_exp_f32_e32 v87, v87
	v_exp_f32_e32 v88, v88
	v_exp_f32_e32 v89, v89
	ds_read_b128 v[190:193], v202
	ds_read_b128 v[186:189], v202 offset:512
	s_waitcnt lgkmcnt(12)
	v_mfma_f32_32x32x16_bf16 v[2:17], v[154:157], v[114:117], v[2:17]
	v_exp_f32_e32 v90, v90
	v_exp_f32_e32 v91, v91
	v_exp_f32_e32 v92, v92
	v_exp_f32_e32 v93, v93
	ds_read_b128 v[182:185], v202 offset:2048
	ds_read_b128 v[178:181], v202 offset:2560
	s_waitcnt lgkmcnt(12)
	v_mfma_f32_32x32x16_bf16 v[18:33], v[154:157], v[118:121], v[18:33]
	v_exp_f32_e32 v94, v94
	v_exp_f32_e32 v95, v95
	v_exp_f32_e32 v96, v96
	v_exp_f32_e32 v97, v97
	ds_read_b128 v[174:177], v202 offset:4096
	ds_read_b128 v[170:173], v202 offset:4608
	s_waitcnt lgkmcnt(12)
	v_mfma_f32_32x32x16_bf16 v[2:17], v[146:149], v[122:125], v[2:17]
	v_exp_f32_e32 v66, v66
	v_exp_f32_e32 v67, v67
	v_exp_f32_e32 v68, v68
	v_exp_f32_e32 v69, v69
	ds_read_b128 v[166:169], v202 offset:6144
	ds_read_b128 v[162:165], v202 offset:6656
	s_waitcnt lgkmcnt(12)
	v_mfma_f32_32x32x16_bf16 v[18:33], v[146:149], v[98:101], v[18:33]
	v_exp_f32_e32 v70, v70
	v_exp_f32_e32 v71, v71
	v_exp_f32_e32 v72, v72
	v_exp_f32_e32 v73, v73
	s_waitcnt lgkmcnt(10)
	v_mfma_f32_32x32x16_bf16 v[2:17], v[142:145], v[102:105], v[2:17]
	v_exp_f32_e32 v74, v74
	v_exp_f32_e32 v75, v75
	v_exp_f32_e32 v76, v76
	v_exp_f32_e32 v77, v77
	s_waitcnt lgkmcnt(8)
	v_mfma_f32_32x32x16_bf16 v[18:33], v[142:145], v[106:109], v[18:33]
	v_exp_f32_e32 v78, v78
	v_exp_f32_e32 v79, v79
	v_exp_f32_e32 v80, v80
	v_exp_f32_e32 v81, v81
	s_add_i32 s6, s31, 0x2000
	s_cmpk_lg_i32 s31, 0x4000
	s_mov_b32 s24, s76
	s_cselect_b32 s76, s6, 0
	s_add_i32 s26, s26, 2
	s_cmp_gt_i32 s26, s91
	s_cbranch_scc1 .Lattn_exit
	s_waitcnt vmcnt(2) lgkmcnt(0)
	s_barrier
.Lattn_cpB:
	ds_read_b64_tr_b16 v[52:53], v201 offset:24576
	ds_read_b64_tr_b16 v[54:55], v201 offset:25088
	v_mfma_f32_32x32x16_bf16 v[114:129], v[190:193], v[150:153], v[34:49]
	v_add_f32_e32 v50, v82, v50
	v_add_f32_e32 v194, v83, v194
	v_add_f32_e32 v195, v84, v195
	v_add_f32_e32 v196, v85, v196
	v_add_f32_e32 v50, v86, v50
	v_add_f32_e32 v194, v87, v194
	v_cvt_pk_bf16_f32 v158, v82, v83
	v_cvt_pk_bf16_f32 v159, v84, v85
	ds_read_b64_tr_b16 v[60:61], v201 offset:28672
	ds_read_b64_tr_b16 v[62:63], v201 offset:29184
	v_mfma_f32_32x32x16_bf16 v[98:113], v[186:189], v[150:153], v[34:49]
	v_add_f32_e32 v195, v88, v195
	v_add_f32_e32 v196, v89, v196
	v_add_f32_e32 v50, v90, v50
	v_add_f32_e32 v194, v91, v194
	v_cvt_pk_bf16_f32 v160, v86, v87
	v_cvt_pk_bf16_f32 v161, v88, v89
	ds_read_b64_tr_b16 v[82:83], v201 offset:25600
	ds_read_b64_tr_b16 v[84:85], v201 offset:26112
	v_mfma_f32_32x32x16_bf16 v[114:129], v[182:185], v[138:141], v[114:129]
	v_add_f32_e32 v195, v92, v195
	v_add_f32_e32 v196, v93, v196
	v_add_f32_e32 v50, v94, v50
	v_add_f32_e32 v194, v95, v194
	v_cvt_pk_bf16_f32 v154, v90, v91
	v_cvt_pk_bf16_f32 v155, v92, v93
	ds_read_b64_tr_b16 v[86:87], v201 offset:29696
	ds_read_b64_tr_b16 v[88:89], v201 offset:30208
	v_mfma_f32_32x32x16_bf16 v[98:113], v[178:181], v[138:141], v[98:113]
	v_add_f32_e32 v195, v96, v195
	v_add_f32_e32 v196, v97, v196
	v_add_f32_e32 v50, v66, v50
	v_add_f32_e32 v194, v67, v194
	v_cvt_pk_bf16_f32 v156, v94, v95
	v_cvt_pk_bf16_f32 v157, v96, v97
	ds_read_b64_tr_b16 v[90:91], v201 offset:26624
	ds_read_b64_tr_b16 v[92:93], v201 offset:27136
	v_mfma_f32_32x32x16_bf16 v[114:129], v[174:177], v[134:137], v[114:129]
	v_add_f32_e32 v195, v68, v195
	v_add_f32_e32 v196, v69, v196
	v_add_f32_e32 v50, v70, v50
	v_add_f32_e32 v194, v71, v194
	v_cvt_pk_bf16_f32 v146, v66, v67
	v_cvt_pk_bf16_f32 v147, v68, v69
	ds_read_b64_tr_b16 v[64:65], v201 offset:30720
	ds_read_b64_tr_b16 v[66:67], v201 offset:31232
	v_mfma_f32_32x32x16_bf16 v[98:113], v[170:173], v[134:137], v[98:113]
	v_add_f32_e32 v195, v72, v195
	v_add_f32_e32 v196, v73, v196
	v_add_f32_e32 v50, v74, v50
	v_add_f32_e32 v194, v75, v194
	v_cvt_pk_bf16_f32 v148, v70, v71
	v_cvt_pk_bf16_f32 v149, v72, v73
	ds_read_b64_tr_b16 v[68:69], v201 offset:27648
	ds_read_b64_tr_b16 v[70:71], v201 offset:28160
	v_mfma_f32_32x32x16_bf16 v[114:129], v[166:169], v[130:133], v[114:129]
	v_add_f32_e32 v195, v76, v195
	v_add_f32_e32 v196, v77, v196
	v_add_f32_e32 v50, v78, v50
	v_add_f32_e32 v194, v79, v194
	v_cvt_pk_bf16_f32 v142, v74, v75
	v_cvt_pk_bf16_f32 v143, v76, v77
	ds_read_b64_tr_b16 v[72:73], v201 offset:31744
	ds_read_b64_tr_b16 v[74:75], v201 offset:32256
	v_mfma_f32_32x32x16_bf16 v[98:113], v[162:165], v[130:133], v[98:113]
	v_add_f32_e32 v195, v80, v195
	v_add_f32_e32 v196, v81, v196
	v_cvt_pk_bf16_f32 v144, v78, v79
	v_cvt_pk_bf16_f32 v145, v80, v81
	s_add_i32 m0, s31, s70
	s_add_i32 s6, s76, s71
	global_load_lds_dwordx4 v197, s[98:99]
	s_mov_b32 m0, s6
	s_nop 0
	global_load_lds_dwordx4 v205, s[98:99]
	s_add_u32 s98, s98, 0x2000
	s_addc_u32 s99, s99, 0
	s_waitcnt lgkmcnt(14)
	v_mfma_f32_32x32x16_bf16 v[2:17], v[158:161], v[52:55], v[2:17]
	v_exp_f32_e32 v114, v114
	v_exp_f32_e32 v115, v115
	v_exp_f32_e32 v116, v116
	v_exp_f32_e32 v117, v117
	s_waitcnt lgkmcnt(12)
	v_mfma_f32_32x32x16_bf16 v[18:33], v[158:161], v[60:63], v[18:33]
	v_exp_f32_e32 v118, v118
	v_exp_f32_e32 v119, v119
	v_exp_f32_e32 v120, v120
	v_exp_f32_e32 v121, v121
	ds_read_b128 v[60:63], v203
	ds_read_b128 v[162:165], v203 offset:512
	s_waitcnt lgkmcnt(12)
	v_mfma_f32_32x32x16_bf16 v[2:17], v[154:157], v[82:85], v[2:17]
	v_exp_f32_e32 v122, v122
	v_exp_f32_e32 v123, v123
	v_exp_f32_e32 v124, v124
	v_exp_f32_e32 v125, v125
	ds_read_b128 v[166:169], v203 offset:2048
	ds_read_b128 v[170:173], v203 offset:2560
	s_waitcnt lgkmcnt(12)
	v_mfma_f32_32x32x16_bf16 v[18:33], v[154:157], v[86:89], v[18:33]
	v_exp_f32_e32 v126, v126
	v_exp_f32_e32 v127, v127
	v_exp_f32_e32 v128, v128
	v_exp_f32_e32 v129, v129
	ds_read_b128 v[174:177], v203 offset:4096
	ds_read_b128 v[178:181], v203 offset:4608
	s_waitcnt lgkmcnt(12)
	v_mfma_f32_32x32x16_bf16 v[2:17], v[146:149], v[90:93], v[2:17]
	v_exp_f32_e32 v98, v98
	v_exp_f32_e32 v99, v99
	v_exp_f32_e32 v100, v100
	v_exp_f32_e32 v101, v101
	ds_read_b128 v[182:185], v203 offset:6144
	ds_read_b128 v[52:55], v203 offset:6656
	s_waitcnt lgkmcnt(12)
	v_mfma_f32_32x32x16_bf16 v[18:33], v[146:149], v[64:67], v[18:33]
	v_exp_f32_e32 v102, v102
	v_exp_f32_e32 v103, v103
	v_exp_f32_e32 v104, v104
	v_exp_f32_e32 v105, v105
	s_waitcnt lgkmcnt(10)
	v_mfma_f32_32x32x16_bf16 v[2:17], v[142:145], v[68:71], v[2:17]
	v_exp_f32_e32 v106, v106
	v_exp_f32_e32 v107, v107
	v_exp_f32_e32 v108, v108
	v_exp_f32_e32 v109, v109
	s_waitcnt lgkmcnt(8)
	v_mfma_f32_32x32x16_bf16 v[18:33], v[142:145], v[72:75], v[18:33]
	v_exp_f32_e32 v110, v110
	v_exp_f32_e32 v111, v111
	v_exp_f32_e32 v112, v112
	v_exp_f32_e32 v113, v113
	s_add_i32 s6, s76, 0x2000
	s_cmpk_lg_i32 s76, 0x4000
	s_cselect_b32 s31, s6, 0
	s_waitcnt vmcnt(2) lgkmcnt(0)
	s_barrier
; #define WAIT_BAR(N) asm volatile("s_waitcnt vmcnt(" #N ") lgkmcnt(0)\n\ts_barrier":::"memory")
;   #define RESC() do{ if(resc){ asm volatile("s_waitcnt lgkmcnt(0)":::"memory"); \
;       _Pragma("unroll") for(int d_=0;d_<2;++d_) _Pragma("unroll") for(int r=0;r<16;++r)o[d_][r]*=wsf[crow(r,hi)]; } }while(0)
;   #define ROT() do{sl_prev=sl_cur;sl_cur=sl_next;sl_next=(sl_next==(NSLOT-1)*SLOTB)?0:sl_next+SLOTB;}while(0)
; template<int THRL> __device__ __forceinline__ void attn_unit(const bf16*Qu,const bf16*__restrict__ Kh,const bf16*__restrict__ Vh,bf16*Ou,const int NT,const float shift,char*shm){
;     ...
;     STEP(pB0,pB1,pA0,pA1,t,true,true,true);     WAIT_BAR(2); RESC(); ROT();
;     STEP(pA0,pA1,pB0,pB1,t+1,true,true,true);   WAIT_BAR(2); RESC(); ROT();
	ds_read_b64_tr_b16 v[186:187], v199 offset:24576
	ds_read_b64_tr_b16 v[188:189], v199 offset:25088
	v_mfma_f32_32x32x16_bf16 v[82:97], v[60:63], v[150:153], v[34:49]
	v_add_f32_e32 v50, v114, v50
	v_add_f32_e32 v194, v115, v194
	v_add_f32_e32 v195, v116, v195
	v_add_f32_e32 v196, v117, v196
	v_add_f32_e32 v50, v118, v50
	v_add_f32_e32 v194, v119, v194
	v_cvt_pk_bf16_f32 v158, v114, v115
	v_cvt_pk_bf16_f32 v159, v116, v117
	ds_read_b64_tr_b16 v[60:61], v199 offset:28672
	ds_read_b64_tr_b16 v[62:63], v199 offset:29184
	v_mfma_f32_32x32x16_bf16 v[66:81], v[162:165], v[150:153], v[34:49]
	v_add_f32_e32 v195, v120, v195
	v_add_f32_e32 v196, v121, v196
	v_add_f32_e32 v50, v122, v50
	v_add_f32_e32 v194, v123, v194
	v_cvt_pk_bf16_f32 v160, v118, v119
	v_cvt_pk_bf16_f32 v161, v120, v121
	ds_read_b64_tr_b16 v[114:115], v199 offset:25600
	ds_read_b64_tr_b16 v[116:117], v199 offset:26112
	v_mfma_f32_32x32x16_bf16 v[82:97], v[166:169], v[138:141], v[82:97]
	v_add_f32_e32 v195, v124, v195
	v_add_f32_e32 v196, v125, v196
	v_add_f32_e32 v50, v126, v50
	v_add_f32_e32 v194, v127, v194
	v_cvt_pk_bf16_f32 v154, v122, v123
	v_cvt_pk_bf16_f32 v155, v124, v125
	ds_read_b64_tr_b16 v[118:119], v199 offset:29696
	ds_read_b64_tr_b16 v[120:121], v199 offset:30208
	v_mfma_f32_32x32x16_bf16 v[66:81], v[170:173], v[138:141], v[66:81]
	v_add_f32_e32 v195, v128, v195
	v_add_f32_e32 v196, v129, v196
	v_add_f32_e32 v50, v98, v50
	v_add_f32_e32 v194, v99, v194
	v_cvt_pk_bf16_f32 v156, v126, v127
	v_cvt_pk_bf16_f32 v157, v128, v129
	ds_read_b64_tr_b16 v[122:123], v199 offset:26624
	ds_read_b64_tr_b16 v[124:125], v199 offset:27136
	v_mfma_f32_32x32x16_bf16 v[82:97], v[174:177], v[134:137], v[82:97]
	v_add_f32_e32 v195, v100, v195
	v_add_f32_e32 v196, v101, v196
	v_add_f32_e32 v50, v102, v50
	v_add_f32_e32 v194, v103, v194
	v_cvt_pk_bf16_f32 v146, v98, v99
	v_cvt_pk_bf16_f32 v147, v100, v101
	ds_read_b64_tr_b16 v[98:99], v199 offset:30720
	ds_read_b64_tr_b16 v[100:101], v199 offset:31232
	v_mfma_f32_32x32x16_bf16 v[66:81], v[178:181], v[134:137], v[66:81]
	v_add_f32_e32 v195, v104, v195
	v_add_f32_e32 v196, v105, v196
	v_add_f32_e32 v50, v106, v50
	v_add_f32_e32 v194, v107, v194
	v_cvt_pk_bf16_f32 v148, v102, v103
	v_cvt_pk_bf16_f32 v149, v104, v105
	ds_read_b64_tr_b16 v[102:103], v199 offset:27648
	ds_read_b64_tr_b16 v[104:105], v199 offset:28160
	v_mfma_f32_32x32x16_bf16 v[82:97], v[182:185], v[130:133], v[82:97]
	v_add_f32_e32 v195, v108, v195
	v_add_f32_e32 v196, v109, v196
	v_add_f32_e32 v50, v110, v50
	v_add_f32_e32 v194, v111, v194
	v_cvt_pk_bf16_f32 v142, v106, v107
	v_cvt_pk_bf16_f32 v143, v108, v109
	ds_read_b64_tr_b16 v[106:107], v199 offset:31744
	ds_read_b64_tr_b16 v[108:109], v199 offset:32256
	v_mfma_f32_32x32x16_bf16 v[66:81], v[52:55], v[130:133], v[66:81]
	v_add_f32_e32 v195, v112, v195
	v_add_f32_e32 v196, v113, v196
	v_cvt_pk_bf16_f32 v144, v110, v111
	v_cvt_pk_bf16_f32 v145, v112, v113
	s_add_i32 m0, s76, s70
	s_add_i32 s6, s31, s71
	global_load_lds_dwordx4 v197, s[98:99]
	s_mov_b32 m0, s6
	s_nop 0
	global_load_lds_dwordx4 v205, s[98:99]
	s_add_u32 s98, s98, 0x2000
	s_addc_u32 s99, s99, 0
	s_waitcnt lgkmcnt(14)
	v_mfma_f32_32x32x16_bf16 v[2:17], v[158:161], v[186:189], v[2:17]
	v_exp_f32_e32 v82, v82
	v_exp_f32_e32 v83, v83
	v_exp_f32_e32 v84, v84
	v_exp_f32_e32 v85, v85
	s_waitcnt lgkmcnt(12)
	v_mfma_f32_32x32x16_bf16 v[18:33], v[158:161], v[60:63], v[18:33]
	v_exp_f32_e32 v86, v86
	v_exp_f32_e32 v87, v87
	v_exp_f32_e32 v88, v88
	v_exp_f32_e32 v89, v89
	ds_read_b128 v[190:193], v204
	ds_read_b128 v[186:189], v204 offset:512
	s_waitcnt lgkmcnt(12)
	v_mfma_f32_32x32x16_bf16 v[2:17], v[154:157], v[114:117], v[2:17]
	v_exp_f32_e32 v90, v90
	v_exp_f32_e32 v91, v91
	v_exp_f32_e32 v92, v92
	v_exp_f32_e32 v93, v93
	ds_read_b128 v[182:185], v204 offset:2048
	ds_read_b128 v[178:181], v204 offset:2560
	s_waitcnt lgkmcnt(12)
	v_mfma_f32_32x32x16_bf16 v[18:33], v[154:157], v[118:121], v[18:33]
	v_exp_f32_e32 v94, v94
	v_exp_f32_e32 v95, v95
	v_exp_f32_e32 v96, v96
	v_exp_f32_e32 v97, v97
	ds_read_b128 v[174:177], v204 offset:4096
	ds_read_b128 v[170:173], v204 offset:4608
	s_waitcnt lgkmcnt(12)
	v_mfma_f32_32x32x16_bf16 v[2:17], v[146:149], v[122:125], v[2:17]
	v_exp_f32_e32 v66, v66
	v_exp_f32_e32 v67, v67
	v_exp_f32_e32 v68, v68
	v_exp_f32_e32 v69, v69
	ds_read_b128 v[166:169], v204 offset:6144
	ds_read_b128 v[162:165], v204 offset:6656
	s_waitcnt lgkmcnt(12)
	v_mfma_f32_32x32x16_bf16 v[18:33], v[146:149], v[98:101], v[18:33]
	v_exp_f32_e32 v70, v70
	v_exp_f32_e32 v71, v71
	v_exp_f32_e32 v72, v72
	v_exp_f32_e32 v73, v73
	s_waitcnt lgkmcnt(10)
	v_mfma_f32_32x32x16_bf16 v[2:17], v[142:145], v[102:105], v[2:17]
	v_exp_f32_e32 v74, v74
	v_exp_f32_e32 v75, v75
	v_exp_f32_e32 v76, v76
	v_exp_f32_e32 v77, v77
	s_waitcnt lgkmcnt(8)
	v_mfma_f32_32x32x16_bf16 v[18:33], v[142:145], v[106:109], v[18:33]
	v_exp_f32_e32 v78, v78
	v_exp_f32_e32 v79, v79
	v_exp_f32_e32 v80, v80
	v_exp_f32_e32 v81, v81
	s_add_i32 s6, s31, 0x2000
	s_cmpk_lg_i32 s31, 0x4000
	s_mov_b32 s24, s76
	s_cselect_b32 s76, s6, 0
	s_add_i32 s26, s26, 2
	s_cmp_gt_i32 s26, s91
	s_cbranch_scc1 .Lattn_exit
	s_waitcnt vmcnt(2) lgkmcnt(0)
	s_barrier
.Lattn_cpC:
	ds_read_b64_tr_b16 v[52:53], v200 offset:24576
	ds_read_b64_tr_b16 v[54:55], v200 offset:25088
	v_mfma_f32_32x32x16_bf16 v[114:129], v[190:193], v[150:153], v[34:49]
	v_add_f32_e32 v50, v82, v50
	v_add_f32_e32 v194, v83, v194
	v_add_f32_e32 v195, v84, v195
	v_add_f32_e32 v196, v85, v196
	v_add_f32_e32 v50, v86, v50
	v_add_f32_e32 v194, v87, v194
	v_cvt_pk_bf16_f32 v158, v82, v83
	v_cvt_pk_bf16_f32 v159, v84, v85
	ds_read_b64_tr_b16 v[60:61], v200 offset:28672
	ds_read_b64_tr_b16 v[62:63], v200 offset:29184
	v_mfma_f32_32x32x16_bf16 v[98:113], v[186:189], v[150:153], v[34:49]
	v_add_f32_e32 v195, v88, v195
	v_add_f32_e32 v196, v89, v196
	v_add_f32_e32 v50, v90, v50
	v_add_f32_e32 v194, v91, v194
	v_cvt_pk_bf16_f32 v160, v86, v87
	v_cvt_pk_bf16_f32 v161, v88, v89
	ds_read_b64_tr_b16 v[82:83], v200 offset:25600
	ds_read_b64_tr_b16 v[84:85], v200 offset:26112
	v_mfma_f32_32x32x16_bf16 v[114:129], v[182:185], v[138:141], v[114:129]
	v_add_f32_e32 v195, v92, v195
	v_add_f32_e32 v196, v93, v196
	v_add_f32_e32 v50, v94, v50
	v_add_f32_e32 v194, v95, v194
	v_cvt_pk_bf16_f32 v154, v90, v91
	v_cvt_pk_bf16_f32 v155, v92, v93
	ds_read_b64_tr_b16 v[86:87], v200 offset:29696
	ds_read_b64_tr_b16 v[88:89], v200 offset:30208
	v_mfma_f32_32x32x16_bf16 v[98:113], v[178:181], v[138:141], v[98:113]
	v_add_f32_e32 v195, v96, v195
	v_add_f32_e32 v196, v97, v196
	v_add_f32_e32 v50, v66, v50
	v_add_f32_e32 v194, v67, v194
	v_cvt_pk_bf16_f32 v156, v94, v95
	v_cvt_pk_bf16_f32 v157, v96, v97
	ds_read_b64_tr_b16 v[90:91], v200 offset:26624
	ds_read_b64_tr_b16 v[92:93], v200 offset:27136
	v_mfma_f32_32x32x16_bf16 v[114:129], v[174:177], v[134:137], v[114:129]
	v_add_f32_e32 v195, v68, v195
	v_add_f32_e32 v196, v69, v196
	v_add_f32_e32 v50, v70, v50
	v_add_f32_e32 v194, v71, v194
	v_cvt_pk_bf16_f32 v146, v66, v67
	v_cvt_pk_bf16_f32 v147, v68, v69
	ds_read_b64_tr_b16 v[64:65], v200 offset:30720
	ds_read_b64_tr_b16 v[66:67], v200 offset:31232
	v_mfma_f32_32x32x16_bf16 v[98:113], v[170:173], v[134:137], v[98:113]
	v_add_f32_e32 v195, v72, v195
	v_add_f32_e32 v196, v73, v196
	v_add_f32_e32 v50, v74, v50
	v_add_f32_e32 v194, v75, v194
	v_cvt_pk_bf16_f32 v148, v70, v71
	v_cvt_pk_bf16_f32 v149, v72, v73
	ds_read_b64_tr_b16 v[68:69], v200 offset:27648
	ds_read_b64_tr_b16 v[70:71], v200 offset:28160
	v_mfma_f32_32x32x16_bf16 v[114:129], v[166:169], v[130:133], v[114:129]
	v_add_f32_e32 v195, v76, v195
	v_add_f32_e32 v196, v77, v196
	v_add_f32_e32 v50, v78, v50
	v_add_f32_e32 v194, v79, v194
	v_cvt_pk_bf16_f32 v142, v74, v75
	v_cvt_pk_bf16_f32 v143, v76, v77
	ds_read_b64_tr_b16 v[72:73], v200 offset:31744
	ds_read_b64_tr_b16 v[74:75], v200 offset:32256
	v_mfma_f32_32x32x16_bf16 v[98:113], v[162:165], v[130:133], v[98:113]
	v_add_f32_e32 v195, v80, v195
	v_add_f32_e32 v196, v81, v196
	v_cvt_pk_bf16_f32 v144, v78, v79
	v_cvt_pk_bf16_f32 v145, v80, v81
	s_add_i32 m0, s31, s70
	s_add_i32 s6, s76, s71
	global_load_lds_dwordx4 v197, s[98:99]
	s_mov_b32 m0, s6
	s_nop 0
	global_load_lds_dwordx4 v205, s[98:99]
	s_add_u32 s98, s98, 0x2000
	s_addc_u32 s99, s99, 0
	s_waitcnt lgkmcnt(14)
	v_mfma_f32_32x32x16_bf16 v[2:17], v[158:161], v[52:55], v[2:17]
	v_exp_f32_e32 v114, v114
	v_exp_f32_e32 v115, v115
	v_exp_f32_e32 v116, v116
	v_exp_f32_e32 v117, v117
	s_waitcnt lgkmcnt(12)
	v_mfma_f32_32x32x16_bf16 v[18:33], v[158:161], v[60:63], v[18:33]
	v_exp_f32_e32 v118, v118
	v_exp_f32_e32 v119, v119
	v_exp_f32_e32 v120, v120
	v_exp_f32_e32 v121, v121
	ds_read_b128 v[60:63], v202
	ds_read_b128 v[162:165], v202 offset:512
	s_waitcnt lgkmcnt(12)
	v_mfma_f32_32x32x16_bf16 v[2:17], v[154:157], v[82:85], v[2:17]
	v_exp_f32_e32 v122, v122
	v_exp_f32_e32 v123, v123
	v_exp_f32_e32 v124, v124
	v_exp_f32_e32 v125, v125
	ds_read_b128 v[166:169], v202 offset:2048
	ds_read_b128 v[170:173], v202 offset:2560
	s_waitcnt lgkmcnt(12)
	v_mfma_f32_32x32x16_bf16 v[18:33], v[154:157], v[86:89], v[18:33]
	v_exp_f32_e32 v126, v126
	v_exp_f32_e32 v127, v127
	v_exp_f32_e32 v128, v128
	v_exp_f32_e32 v129, v129
	ds_read_b128 v[174:177], v202 offset:4096
	ds_read_b128 v[178:181], v202 offset:4608
	s_waitcnt lgkmcnt(12)
	v_mfma_f32_32x32x16_bf16 v[2:17], v[146:149], v[90:93], v[2:17]
	v_exp_f32_e32 v98, v98
	v_exp_f32_e32 v99, v99
	v_exp_f32_e32 v100, v100
	v_exp_f32_e32 v101, v101
	ds_read_b128 v[182:185], v202 offset:6144
	ds_read_b128 v[52:55], v202 offset:6656
	s_waitcnt lgkmcnt(12)
	v_mfma_f32_32x32x16_bf16 v[18:33], v[146:149], v[64:67], v[18:33]
	v_exp_f32_e32 v102, v102
	v_exp_f32_e32 v103, v103
	v_exp_f32_e32 v104, v104
	v_exp_f32_e32 v105, v105
	s_waitcnt lgkmcnt(10)
	v_mfma_f32_32x32x16_bf16 v[2:17], v[142:145], v[68:71], v[2:17]
	v_exp_f32_e32 v106, v106
	v_exp_f32_e32 v107, v107
	v_exp_f32_e32 v108, v108
	v_exp_f32_e32 v109, v109
	s_waitcnt lgkmcnt(8)
	v_mfma_f32_32x32x16_bf16 v[18:33], v[142:145], v[72:75], v[18:33]
	v_exp_f32_e32 v110, v110
	v_exp_f32_e32 v111, v111
	v_exp_f32_e32 v112, v112
	v_exp_f32_e32 v113, v113
	s_add_i32 s6, s76, 0x2000
	s_cmpk_lg_i32 s76, 0x4000
	s_cselect_b32 s31, s6, 0
	s_waitcnt vmcnt(2) lgkmcnt(0)
	s_barrier
; #define WAIT_BAR(N) asm volatile("s_waitcnt vmcnt(" #N ") lgkmcnt(0)\n\ts_barrier":::"memory")
;   #define RESC() do{ if(resc){ asm volatile("s_waitcnt lgkmcnt(0)":::"memory"); \
;       _Pragma("unroll") for(int d_=0;d_<2;++d_) _Pragma("unroll") for(int r=0;r<16;++r)o[d_][r]*=wsf[crow(r,hi)]; } }while(0)
;   #define ROT() do{sl_prev=sl_cur;sl_cur=sl_next;sl_next=(sl_next==(NSLOT-1)*SLOTB)?0:sl_next+SLOTB;}while(0)
; template<int THRL> __device__ __forceinline__ void attn_unit(const bf16*Qu,const bf16*__restrict__ Kh,const bf16*__restrict__ Vh,bf16*Ou,const int NT,const float shift,char*shm){
;     ...
;   for(;t+5<NT;t+=2){
;     STEP(pB0,pB1,pA0,pA1,t,true,true,true);     WAIT_BAR(2); RESC(); ROT();
;     STEP(pA0,pA1,pB0,pB1,t+1,true,true,true);   WAIT_BAR(2); RESC(); ROT();
;   }
	ds_read_b64_tr_b16 v[186:187], v201 offset:24576
	ds_read_b64_tr_b16 v[188:189], v201 offset:25088
	v_mfma_f32_32x32x16_bf16 v[82:97], v[60:63], v[150:153], v[34:49]
	v_add_f32_e32 v50, v114, v50
	v_add_f32_e32 v194, v115, v194
	v_add_f32_e32 v195, v116, v195
	v_add_f32_e32 v196, v117, v196
	v_add_f32_e32 v50, v118, v50
	v_add_f32_e32 v194, v119, v194
	v_cvt_pk_bf16_f32 v158, v114, v115
	v_cvt_pk_bf16_f32 v159, v116, v117
	ds_read_b64_tr_b16 v[60:61], v201 offset:28672
	ds_read_b64_tr_b16 v[62:63], v201 offset:29184
	v_mfma_f32_32x32x16_bf16 v[66:81], v[162:165], v[150:153], v[34:49]
	v_add_f32_e32 v195, v120, v195
	v_add_f32_e32 v196, v121, v196
	v_add_f32_e32 v50, v122, v50
	v_add_f32_e32 v194, v123, v194
	v_cvt_pk_bf16_f32 v160, v118, v119
	v_cvt_pk_bf16_f32 v161, v120, v121
	ds_read_b64_tr_b16 v[114:115], v201 offset:25600
	ds_read_b64_tr_b16 v[116:117], v201 offset:26112
	v_mfma_f32_32x32x16_bf16 v[82:97], v[166:169], v[138:141], v[82:97]
	v_add_f32_e32 v195, v124, v195
	v_add_f32_e32 v196, v125, v196
	v_add_f32_e32 v50, v126, v50
	v_add_f32_e32 v194, v127, v194
	v_cvt_pk_bf16_f32 v154, v122, v123
	v_cvt_pk_bf16_f32 v155, v124, v125
	ds_read_b64_tr_b16 v[118:119], v201 offset:29696
	ds_read_b64_tr_b16 v[120:121], v201 offset:30208
	v_mfma_f32_32x32x16_bf16 v[66:81], v[170:173], v[138:141], v[66:81]
	v_add_f32_e32 v195, v128, v195
	v_add_f32_e32 v196, v129, v196
	v_add_f32_e32 v50, v98, v50
	v_add_f32_e32 v194, v99, v194
	v_cvt_pk_bf16_f32 v156, v126, v127
	v_cvt_pk_bf16_f32 v157, v128, v129
	ds_read_b64_tr_b16 v[122:123], v201 offset:26624
	ds_read_b64_tr_b16 v[124:125], v201 offset:27136
	v_mfma_f32_32x32x16_bf16 v[82:97], v[174:177], v[134:137], v[82:97]
	v_add_f32_e32 v195, v100, v195
	v_add_f32_e32 v196, v101, v196
	v_add_f32_e32 v50, v102, v50
	v_add_f32_e32 v194, v103, v194
	v_cvt_pk_bf16_f32 v146, v98, v99
	v_cvt_pk_bf16_f32 v147, v100, v101
	ds_read_b64_tr_b16 v[98:99], v201 offset:30720
	ds_read_b64_tr_b16 v[100:101], v201 offset:31232
	v_mfma_f32_32x32x16_bf16 v[66:81], v[178:181], v[134:137], v[66:81]
	v_add_f32_e32 v195, v104, v195
	v_add_f32_e32 v196, v105, v196
	v_add_f32_e32 v50, v106, v50
	v_add_f32_e32 v194, v107, v194
	v_cvt_pk_bf16_f32 v148, v102, v103
	v_cvt_pk_bf16_f32 v149, v104, v105
	ds_read_b64_tr_b16 v[102:103], v201 offset:27648
	ds_read_b64_tr_b16 v[104:105], v201 offset:28160
	v_mfma_f32_32x32x16_bf16 v[82:97], v[182:185], v[130:133], v[82:97]
	v_add_f32_e32 v195, v108, v195
	v_add_f32_e32 v196, v109, v196
	v_add_f32_e32 v50, v110, v50
	v_add_f32_e32 v194, v111, v194
	v_cvt_pk_bf16_f32 v142, v106, v107
	v_cvt_pk_bf16_f32 v143, v108, v109
	ds_read_b64_tr_b16 v[106:107], v201 offset:31744
	ds_read_b64_tr_b16 v[108:109], v201 offset:32256
	v_mfma_f32_32x32x16_bf16 v[66:81], v[52:55], v[130:133], v[66:81]
	v_add_f32_e32 v195, v112, v195
	v_add_f32_e32 v196, v113, v196
	v_cvt_pk_bf16_f32 v144, v110, v111
	v_cvt_pk_bf16_f32 v145, v112, v113
	s_add_i32 m0, s76, s70
	s_add_i32 s6, s31, s71
	global_load_lds_dwordx4 v197, s[98:99]
	s_mov_b32 m0, s6
	s_nop 0
	global_load_lds_dwordx4 v205, s[98:99]
	s_add_u32 s98, s98, 0x2000
	s_addc_u32 s99, s99, 0
	s_waitcnt lgkmcnt(14)
	v_mfma_f32_32x32x16_bf16 v[2:17], v[158:161], v[186:189], v[2:17]
	v_exp_f32_e32 v82, v82
	v_exp_f32_e32 v83, v83
	v_exp_f32_e32 v84, v84
	v_exp_f32_e32 v85, v85
	s_waitcnt lgkmcnt(12)
	v_mfma_f32_32x32x16_bf16 v[18:33], v[158:161], v[60:63], v[18:33]
	v_exp_f32_e32 v86, v86
	v_exp_f32_e32 v87, v87
	v_exp_f32_e32 v88, v88
	v_exp_f32_e32 v89, v89
	ds_read_b128 v[190:193], v203
	ds_read_b128 v[186:189], v203 offset:512
	s_waitcnt lgkmcnt(12)
	v_mfma_f32_32x32x16_bf16 v[2:17], v[154:157], v[114:117], v[2:17]
	v_exp_f32_e32 v90, v90
	v_exp_f32_e32 v91, v91
	v_exp_f32_e32 v92, v92
	v_exp_f32_e32 v93, v93
	ds_read_b128 v[182:185], v203 offset:2048
	ds_read_b128 v[178:181], v203 offset:2560
	s_waitcnt lgkmcnt(12)
	v_mfma_f32_32x32x16_bf16 v[18:33], v[154:157], v[118:121], v[18:33]
	v_exp_f32_e32 v94, v94
	v_exp_f32_e32 v95, v95
	v_exp_f32_e32 v96, v96
	v_exp_f32_e32 v97, v97
	ds_read_b128 v[174:177], v203 offset:4096
	ds_read_b128 v[170:173], v203 offset:4608
	s_waitcnt lgkmcnt(12)
	v_mfma_f32_32x32x16_bf16 v[2:17], v[146:149], v[122:125], v[2:17]
	v_exp_f32_e32 v66, v66
	v_exp_f32_e32 v67, v67
	v_exp_f32_e32 v68, v68
	v_exp_f32_e32 v69, v69
	ds_read_b128 v[166:169], v203 offset:6144
	ds_read_b128 v[162:165], v203 offset:6656
	s_waitcnt lgkmcnt(12)
	v_mfma_f32_32x32x16_bf16 v[18:33], v[146:149], v[98:101], v[18:33]
	v_exp_f32_e32 v70, v70
	v_exp_f32_e32 v71, v71
	v_exp_f32_e32 v72, v72
	v_exp_f32_e32 v73, v73
	s_waitcnt lgkmcnt(10)
	v_mfma_f32_32x32x16_bf16 v[2:17], v[142:145], v[102:105], v[2:17]
	v_exp_f32_e32 v74, v74
	v_exp_f32_e32 v75, v75
	v_exp_f32_e32 v76, v76
	v_exp_f32_e32 v77, v77
	s_waitcnt lgkmcnt(8)
	v_mfma_f32_32x32x16_bf16 v[18:33], v[142:145], v[106:109], v[18:33]
	v_exp_f32_e32 v78, v78
	v_exp_f32_e32 v79, v79
	v_exp_f32_e32 v80, v80
	v_exp_f32_e32 v81, v81
	s_add_i32 s6, s31, 0x2000
	s_cmpk_lg_i32 s31, 0x4000
	s_mov_b32 s24, s76
	s_cselect_b32 s76, s6, 0
	s_add_i32 s26, s26, 2
	s_cmp_gt_i32 s26, s91
	s_cbranch_scc0 .Lattn_rot
